# m3: BOG/mng loads issued after the last prologue vmcnt wait (before barrier 1) so S and PV stages cover their latency
# speedup vs baseline: 1.0018x; 1.0018x over previous
.LBB0_472:
	s_or_b64 exec, exec, s[2:3]
	s_waitcnt vmcnt(0)
	s_lshr_b32 s90, s40, 6
	s_lshl_b32 s90, s90, 3
	s_add_u32 s90, s34, s90
	s_addc_u32 s91, s35, 0
	s_lshl_b64 s[90:91], s[90:91], 11
	s_add_u32 s90, s22, s90
	s_addc_u32 s91, s23, s91
	s_lshl_b32 s92, s12, 1
	v_and_b32_e32 v232, 63, v23
	v_lshlrev_b32_e32 v233, 3, v232
	v_lshl_or_b32 v232, v232, 2, s92
	global_load_dword v224, v232, s[90:91]
	global_load_dword v225, v232, s[90:91] offset:2048
	s_add_u32 s90, s90, 0x1000
	s_addc_u32 s91, s91, 0
	global_load_dword v226, v232, s[90:91]
	global_load_dword v227, v232, s[90:91] offset:2048
	s_add_u32 s90, s90, 0x1000
	s_addc_u32 s91, s91, 0
	global_load_dword v228, v232, s[90:91]
	global_load_dword v229, v232, s[90:91] offset:2048
	s_add_u32 s90, s90, 0x1000
	s_addc_u32 s91, s91, 0
	global_load_dword v230, v232, s[90:91]
	global_load_dword v231, v232, s[90:91] offset:2048
	global_load_dwordx2 v[234:235], v233, s[20:21]
	v_mul_f32_e32 v8, 0xbfb8aa3b, v4
	v_exp_f32_e32 v8, v8
	s_bfe_u32 s5, s40, 0x20006
	v_and_b32_e32 v9, 15, v23
	s_ashr_i32 s6, s40, 7
	v_add_f32_e32 v8, 1.0, v8
	v_rcp_f32_e32 v10, v8
	v_mul_f32_e32 v8, 0xbfb8aa3b, v5
	v_exp_f32_e32 v8, v8
	s_lshl_b32 s4, s5, 4
	s_and_b32 s2, s6, -2
	s_cmp_gt_i32 s2, s5
	v_add_f32_e32 v8, 1.0, v8
	v_rcp_f32_e32 v11, v8
	v_mul_f32_e32 v8, 0xbfb8aa3b, v6
	v_exp_f32_e32 v8, v8
	v_pk_mul_f32 v[4:5], v[4:5], v[10:11]
	v_add_f32_e32 v8, 1.0, v8
	v_rcp_f32_e32 v10, v8
	v_mul_f32_e32 v8, 0xbfb8aa3b, v7
	v_exp_f32_e32 v8, v8
	s_nop 0
	v_add_f32_e32 v8, 1.0, v8
	v_rcp_f32_e32 v11, v8
	v_mul_f32_e32 v8, 0xbfb8aa3b, v0
	v_exp_f32_e32 v8, v8
	v_pk_mul_f32 v[6:7], v[6:7], v[10:11]
	v_add_f32_e32 v8, 1.0, v8
	v_rcp_f32_e32 v10, v8
	v_mul_f32_e32 v8, 0xbfb8aa3b, v1
	v_exp_f32_e32 v8, v8
	s_nop 0
	v_add_f32_e32 v8, 1.0, v8
	v_rcp_f32_e32 v11, v8
	s_nop 0
	v_pk_mul_f32 v[10:11], v[0:1], v[10:11]
	v_mul_f32_e32 v0, 0xbfb8aa3b, v2
	v_mul_f32_e32 v1, 0xbfb8aa3b, v3
	v_exp_f32_e32 v0, v0
	v_exp_f32_e32 v1, v1
	v_add_f32_e32 v0, 1.0, v0
	v_add_f32_e32 v1, 1.0, v1
	v_rcp_f32_e32 v0, v0
	v_rcp_f32_e32 v1, v1
	s_nop 0
	v_pk_mul_f32 v[12:13], v[2:3], v[0:1]
	v_cvt_pk_bf16_f32 v0, v4, v5
	v_cvt_pk_bf16_f32 v1, v6, v7
	v_cvt_pk_bf16_f32 v2, v10, v11
	v_cvt_pk_bf16_f32 v3, v12, v13
	ds_write_b128 v24, v[0:3] offset:9216
	v_and_b32_e32 v1, 48, v22
	v_or_b32_e32 v0, s4, v9
	v_add_u32_e32 v8, 0, v1
	v_mad_u32_u24 v10, v0, s84, v8
	v_lshl_or_b32 v12, s2, 4, v9
	v_mov_b32_e32 v5, 0
	v_mov_b32_e32 v0, 0
	v_mov_b32_e32 v1, 0
	v_mov_b32_e32 v2, 0
	v_mov_b32_e32 v3, 0
	s_waitcnt lgkmcnt(0)
	s_barrier
	s_cbranch_scc1 .LBB0_474
	v_mad_u64_u32 v[6:7], s[2:3], v12, s84, v[8:9]
	ds_read_b128 v[0:3], v10
	ds_read_b128 v[14:17], v6 offset:9216
	s_waitcnt lgkmcnt(0)
	v_mfma_f32_16x16x32_bf16 v[0:3], v[0:3], v[14:17], 0
	ds_read_b128 v[14:17], v10 offset:64
	ds_read_b128 v[18:21], v6 offset:9280
	s_waitcnt lgkmcnt(0)
	v_mfma_f32_16x16x32_bf16 v[0:3], v[14:17], v[18:21], v[0:3]
